# sample-attention wave runs at raised priority next to the LRU final-pass waves
# baseline (speedup 1.0000x reference)
.LBB0_1185:
	s_or_b64 exec, exec, s[0:1]
	v_readlane_b32 s0, v254, 10
	v_readlane_b32 s2, v254, 12
	v_readlane_b32 s1, v254, 11
	s_bitcmp0_b32 s2, 1
	s_cselect_b64 s[0:1], -1, 0
	s_and_b32 s2, s97, 7
	v_readlane_b32 s3, v254, 13
	s_cmp_lg_u32 s60, s2
	s_cselect_b64 s[2:3], -1, 0
	s_or_b64 s[0:1], s[0:1], s[2:3]
	s_cmpk_gt_i32 s97, 0xff
	s_cselect_b64 s[2:3], -1, 0
	s_or_b64 s[0:1], s[2:3], s[0:1]
	s_and_b64 vcc, exec, s[0:1]
	s_waitcnt lgkmcnt(0)
	s_barrier
	s_cbranch_vccnz .LBB0_1207
	s_setprio 3
	v_and_b32_e32 v3, 15, v0
	v_and_b32_e32 v8, 48, v1
	v_mov_b32_e32 v2, 0
	v_lshl_or_b32 v4, v3, 8, v8
	v_mov_b32_e32 v5, v2
	v_lshl_or_b32 v200, v3, 6, v8
	v_mov_b32_e32 v201, v2
	v_lshrrev_b32_e32 v6, 4, v1
	v_lshl_add_u64 v[198:199], s[6:7], 0, v[4:5]
	v_lshl_add_u64 v[4:5], s[76:77], 0, v[200:201]
	s_mov_b64 s[0:1], 0x24000000
	v_lshlrev_b32_e32 v7, 3, v6
	v_and_or_b32 v9, v175, 24, v174
	v_lshl_add_u64 v[202:203], v[4:5], 0, s[0:1]
	v_lshlrev_b32_e32 v4, 12, v3
	v_or_b32_e32 v10, 0x201, v7
	v_or_b32_e32 v11, 0x203, v7
	v_or_b32_e32 v12, 0x205, v7
	v_or_b32_e32 v13, 0x207, v7
	v_lshl_or_b32 v204, v6, 2, v4
	v_lshl_or_b32 v4, v9, 8, v8
	v_mov_b32_e32 v5, v2
	v_or_b32_e32 v6, 0x1e1, v7
	v_or_b32_e32 v8, 0x1e3, v7
	v_or_b32_e32 v9, 0x1e5, v7
	v_or_b32_e32 v14, 0x1e7, v7
	v_sub_u32_e32 v201, v3, v7
	v_lshl_add_u64 v[206:207], s[4:5], 0, v[4:5]
	v_lshl_add_u64 v[4:5], s[76:77], 0, v[4:5]
	s_mov_b64 s[0:1], 0x20000000
	v_sub_u32_e32 v211, v3, v6
	v_sub_u32_e32 v222, v3, v8
	v_sub_u32_e32 v223, v3, v9
	v_sub_u32_e32 v224, v3, v14
	v_sub_u32_e32 v225, v3, v10
	v_sub_u32_e32 v226, v3, v11
	v_sub_u32_e32 v227, v3, v12
	v_sub_u32_e32 v228, v3, v13
	v_lshlrev_b32_e32 v3, 8, v0
	v_lshl_add_u64 v[208:209], v[4:5], 0, s[0:1]
	v_and_b32_e32 v3, 0xc00, v3
	v_lshlrev_b32_e32 v4, 7, v174
	v_or3_b32 v3, v3, v4, v7
	v_mov_b32_e32 v205, v2
	v_lshlrev_b32_e32 v210, 1, v3
	s_movk_i32 s10, 0x1000
	v_mov_b32_e32 v229, 0x22000
	s_mov_b32 s11, 0x20002000
	s_mov_b32 s12, 0x24002000
	s_mov_b32 s13, 0x24003000
	s_mov_b32 s14, 0x20000
	s_mov_b32 s15, 0x21000
	s_mov_b64 s[0:1], 0x2000000
	s_mov_b32 s18, 0xc3e00000
	s_brev_b32 s19, 64
	s_mov_b32 s24, 0x2010000
	v_mov_b32_e32 v230, 0x43e00000
	s_mov_b32 s2, s97
	s_branch .LBB0_1188

.LBB0_1207:
	s_setprio 0
	v_readlane_b32 s0, v254, 10
	v_readlane_b32 s2, v254, 12
	s_and_b32 s0, s2, 8
	s_bitcmp1_b32 s2, 3
	s_cselect_b64 s[8:9], -1, 0
	s_cmp_eq_u32 s0, 0
	v_readlane_b32 s1, v254, 11
	v_readlane_b32 s3, v254, 13
	s_cbranch_scc1 .LBB0_1250
	s_abs_i32 s0, s96
	v_cvt_f32_u32_e32 v2, s0
	s_sub_i32 s5, 0, s0
	s_add_i32 s1, s96, 0x3fff
	s_xor_b32 s4, s1, s96
	v_rcp_iflag_f32_e32 v2, v2
	s_abs_i32 s1, s1
	s_ashr_i32 s4, s4, 31
	v_cmp_eq_u32_e64 s[2:3], 0, v1
	v_mul_f32_e32 v2, 0x4f7ffffe, v2
	v_cvt_u32_f32_e32 v2, v2
	v_mov_b32_e32 v19, 0
	s_mov_b64 s[10:11], 0x10000
	s_mov_b64 s[12:13], 0x11000
	v_readfirstlane_b32 s6, v2
	s_mul_i32 s5, s5, s6
	s_mul_hi_u32 s5, s6, s5
	s_add_i32 s6, s6, s5
	s_mul_hi_u32 s5, s1, s6
	s_mul_i32 s6, s5, s0
	s_sub_i32 s1, s1, s6
	s_add_i32 s7, s5, 1
	s_sub_i32 s6, s1, s0
	s_cmp_ge_u32 s1, s0
	s_cselect_b32 s5, s7, s5
	s_cselect_b32 s1, s6, s1
	s_add_i32 s6, s5, 1
	s_cmp_ge_u32 s1, s0
	s_cselect_b32 s0, s6, s5
	s_xor_b32 s0, s0, s4
	s_sub_i32 s0, s0, s4
	s_mul_i32 s33, s0, s97
	s_add_i32 s0, s33, s0
	s_min_i32 s37, s0, 0x4000
	s_add_u32 s42, s76, 0x44b00000
	s_addc_u32 s43, s77, 0
	s_add_u32 s50, s76, 0x2a600000
	s_addc_u32 s51, s77, 0
	s_add_u32 s52, s76, 0x300000
	v_mbcnt_lo_u32_b32 v2, -1, 0
	s_addc_u32 s53, s77, 0
	s_add_i32 s54, 0, 0x22044
	s_mov_b64 s[14:15], 0x12000
	s_mov_b64 s[16:17], 0x13000
	s_mov_b64 s[18:19], 0x20000
	s_mov_b64 s[24:25], 0x21000
	s_mov_b64 s[26:27], 0x22000
	s_mov_b64 s[28:29], 0x23000
	s_mov_b64 s[30:31], 0x30000
	s_mov_b64 s[34:35], 0x31000
	s_mov_b64 s[38:39], 0x32000
	s_mov_b64 s[40:41], 0x33000
	s_mov_b32 s55, 0xc3e00000
	s_mov_b64 s[44:45], 0x2c800800
	v_mbcnt_hi_u32_b32 v90, -1, v2
	v_mov_b32_e32 v91, 0x43e00000
	s_branch .LBB0_1211
